# v9 + hand-written R1, padded so later code keeps v9 byte alignment mod 256
# baseline (speedup 1.0000x reference)
.LBB0_172:
	s_cmp_lt_i32 s96, 2
	s_cselect_b64 s[4:5], -1, 0
	s_lshl_b32 s54, s2, 3
	s_and_b64 s[4:5], s[4:5], s[0:1]
	s_add_i32 s44, s89, s54
	s_andn2_b64 vcc, exec, s[4:5]
	s_lshl_b32 s48, s33, 4
	s_cbranch_vccnz .LBB0_181
	s_cmpk_gt_i32 s44, 0x1fff
	s_cbranch_scc1 .LBB0_181
	s_mov_b32 s34, s89
	v_readlane_b32 s6, v254, 6
	v_readlane_b32 s7, v254, 7
	v_readlane_b32 s8, v254, 8
	v_readlane_b32 s9, v254, 9
	v_readlane_b32 s10, v254, 20
	v_readlane_b32 s11, v254, 21
	v_lshlrev_b32_e32 v230, 5, v191
	v_lshlrev_b32_e32 v231, 4, v191
	v_mov_b32_e32 v246, 0x3a000000
	s_nop 1
	s_lshl_b32 s12, s44, 1
	s_lshl_b32 s13, s12, 13
	s_add_u32 s14, s6, s13
	s_addc_u32 s15, s7, 0
	s_add_u32 s16, s8, s13
	s_addc_u32 s17, s9, 0
	s_and_b32 s18, s12, 1023
	s_lshr_b32 s19, s12, 10
	s_add_u32 s20, s10, 0x1000
	s_addc_u32 s21, s11, 0
	s_lshl_b32 s22, s12, 12
	s_add_u32 s22, s22, 0x4800000
	s_add_u32 s22, s62, s22
	s_addc_u32 s23, s63, 0
	global_load_dwordx4 v[130:133], v230, s[10:11]
	global_load_dwordx4 v[134:137], v230, s[10:11] offset:16
	global_load_dwordx4 v[138:141], v230, s[10:11] offset:2048
	global_load_dwordx4 v[142:145], v230, s[10:11] offset:2064
	global_load_dwordx4 v[146:149], v230, s[20:21]
	global_load_dwordx4 v[150:153], v230, s[20:21] offset:16
	global_load_dwordx4 v[154:157], v230, s[20:21] offset:2048
	global_load_dwordx4 v[158:161], v230, s[20:21] offset:2064
	s_add_u32 s26, s14, 0
	s_addc_u32 s27, s15, 0
	s_add_u32 s24, s26, 0x1000
	s_addc_u32 s25, s27, 0
	global_load_dwordx4 v[2:5], v230, s[26:27] nt
	global_load_dwordx4 v[6:9], v230, s[26:27] offset:16 nt
	global_load_dwordx4 v[10:13], v230, s[26:27] offset:2048 nt
	global_load_dwordx4 v[14:17], v230, s[26:27] offset:2064 nt
	global_load_dwordx4 v[18:21], v230, s[24:25] nt
	global_load_dwordx4 v[22:25], v230, s[24:25] offset:16 nt
	global_load_dwordx4 v[26:29], v230, s[24:25] offset:2048 nt
	global_load_dwordx4 v[30:33], v230, s[24:25] offset:2064 nt
	s_mov_b32 s38, 0
	s_add_u32 s38, s62, s38
	s_addc_u32 s39, s63, 0
	s_add_u32 s40, s38, 0x2000
	s_addc_u32 s41, s39, 0
	s_add_u32 s64, s38, 0x1000
	s_addc_u32 s65, s39, 0
	s_add_u32 s66, s40, 0x1000
	s_addc_u32 s67, s41, 0
	global_load_dwordx4 v[194:197], v230, s[38:39]
	global_load_dwordx4 v[162:165], v230, s[40:41]
	global_load_dwordx4 v[198:201], v230, s[38:39] offset:16
	global_load_dwordx4 v[166:169], v230, s[40:41] offset:16
	global_load_dwordx4 v[202:205], v230, s[38:39] offset:2048
	global_load_dwordx4 v[170:173], v230, s[40:41] offset:2048
	global_load_dwordx4 v[206:209], v230, s[38:39] offset:2064
	global_load_dwordx4 v[174:177], v230, s[40:41] offset:2064
	global_load_dwordx4 v[210:213], v230, s[64:65]
	global_load_dwordx4 v[178:181], v230, s[66:67]
	global_load_dwordx4 v[214:217], v230, s[64:65] offset:16
	global_load_dwordx4 v[182:185], v230, s[66:67] offset:16
	global_load_dwordx4 v[218:221], v230, s[64:65] offset:2048
	global_load_dwordx4 v[186:189], v230, s[66:67] offset:2048
	global_load_dwordx4 v[222:225], v230, s[64:65] offset:2064
	global_load_dwordx4 v[226:229], v230, s[66:67] offset:2064
	s_add_u32 s26, s14, 8192
	s_addc_u32 s27, s15, 0
	s_add_u32 s24, s26, 0x1000
	s_addc_u32 s25, s27, 0
	global_load_dwordx4 v[34:37], v230, s[26:27] nt
	global_load_dwordx4 v[38:41], v230, s[26:27] offset:16 nt
	global_load_dwordx4 v[42:45], v230, s[26:27] offset:2048 nt
	global_load_dwordx4 v[46:49], v230, s[26:27] offset:2064 nt
	global_load_dwordx4 v[50:53], v230, s[24:25] nt
	global_load_dwordx4 v[54:57], v230, s[24:25] offset:16 nt
	global_load_dwordx4 v[58:61], v230, s[24:25] offset:2048 nt
	global_load_dwordx4 v[62:65], v230, s[24:25] offset:2064 nt
	s_add_u32 s26, s14, 33554432
	s_addc_u32 s27, s15, 0
	s_add_u32 s24, s26, 0x1000
	s_addc_u32 s25, s27, 0
	global_load_dwordx4 v[66:69], v230, s[26:27] nt
	global_load_dwordx4 v[70:73], v230, s[26:27] offset:16 nt
	global_load_dwordx4 v[74:77], v230, s[26:27] offset:2048 nt
	global_load_dwordx4 v[78:81], v230, s[26:27] offset:2064 nt
	global_load_dwordx4 v[82:85], v230, s[24:25] nt
	global_load_dwordx4 v[86:89], v230, s[24:25] offset:16 nt
	global_load_dwordx4 v[90:93], v230, s[24:25] offset:2048 nt
	global_load_dwordx4 v[94:97], v230, s[24:25] offset:2064 nt
	s_waitcnt vmcnt(32)
	v_pk_mul_f32 v[232:233], v[2:3], v[2:3]
	v_pk_fma_f32 v[232:233], v[4:5], v[4:5], v[232:233]
	v_pk_fma_f32 v[232:233], v[6:7], v[6:7], v[232:233]
	v_pk_fma_f32 v[232:233], v[8:9], v[8:9], v[232:233]
	v_pk_fma_f32 v[232:233], v[10:11], v[10:11], v[232:233]
	v_pk_fma_f32 v[232:233], v[12:13], v[12:13], v[232:233]
	v_pk_fma_f32 v[232:233], v[14:15], v[14:15], v[232:233]
	v_pk_fma_f32 v[232:233], v[16:17], v[16:17], v[232:233]
	v_pk_fma_f32 v[232:233], v[18:19], v[18:19], v[232:233]
	v_pk_fma_f32 v[232:233], v[20:21], v[20:21], v[232:233]
	v_pk_fma_f32 v[232:233], v[22:23], v[22:23], v[232:233]
	v_pk_fma_f32 v[232:233], v[24:25], v[24:25], v[232:233]
	v_pk_fma_f32 v[232:233], v[26:27], v[26:27], v[232:233]
	v_pk_fma_f32 v[232:233], v[28:29], v[28:29], v[232:233]
	v_pk_fma_f32 v[232:233], v[30:31], v[30:31], v[232:233]
	v_pk_fma_f32 v[232:233], v[32:33], v[32:33], v[232:233]
	v_add_f32_e32 v232, v232, v233
	s_nop 1
	v_add_f32_dpp v232, v232, v232 quad_perm:[1,0,3,2] row_mask:0xf bank_mask:0xf
	s_nop 1
	v_add_f32_dpp v232, v232, v232 quad_perm:[2,3,0,1] row_mask:0xf bank_mask:0xf
	s_nop 1
	v_add_f32_dpp v232, v232, v232 row_half_mirror row_mask:0xf bank_mask:0xf
	s_nop 1
	v_add_f32_dpp v232, v232, v232 row_mirror row_mask:0xf bank_mask:0xf
	s_nop 1
	v_readlane_b32 s0, v232, 0
	v_readlane_b32 s1, v232, 16
	v_readlane_b32 s68, v232, 32
	v_readlane_b32 s69, v232, 48
	s_nop 3
	v_mov_b32_e32 v234, s0
	v_add_f32_e32 v234, s1, v234
	v_add_f32_e32 v234, s68, v234
	v_add_f32_e32 v234, s69, v234
	v_fmaak_f32 v234, v234, v246, 0x358637bd
	v_rsq_f32_e32 v234, v234
	s_nop 0
	v_mov_b32_e32 v235, v234
	s_waitcnt vmcnt(16)
	v_pk_add_f32 v[162:163], v[162:163], 1.0 op_sel_hi:[1,0]
	v_pk_add_f32 v[164:165], v[164:165], 1.0 op_sel_hi:[1,0]
	v_pk_add_f32 v[166:167], v[166:167], 1.0 op_sel_hi:[1,0]
	v_pk_add_f32 v[168:169], v[168:169], 1.0 op_sel_hi:[1,0]
	v_pk_add_f32 v[170:171], v[170:171], 1.0 op_sel_hi:[1,0]
	v_pk_add_f32 v[172:173], v[172:173], 1.0 op_sel_hi:[1,0]
	v_pk_add_f32 v[174:175], v[174:175], 1.0 op_sel_hi:[1,0]
	v_pk_add_f32 v[176:177], v[176:177], 1.0 op_sel_hi:[1,0]
	v_pk_add_f32 v[178:179], v[178:179], 1.0 op_sel_hi:[1,0]
	v_pk_add_f32 v[180:181], v[180:181], 1.0 op_sel_hi:[1,0]
	v_pk_add_f32 v[182:183], v[182:183], 1.0 op_sel_hi:[1,0]
	v_pk_add_f32 v[184:185], v[184:185], 1.0 op_sel_hi:[1,0]
	v_pk_add_f32 v[186:187], v[186:187], 1.0 op_sel_hi:[1,0]
	v_pk_add_f32 v[188:189], v[188:189], 1.0 op_sel_hi:[1,0]
	v_pk_add_f32 v[226:227], v[226:227], 1.0 op_sel_hi:[1,0]
	v_pk_add_f32 v[228:229], v[228:229], 1.0 op_sel_hi:[1,0]
	s_add_u32 s70, s22, 0
	s_addc_u32 s71, s23, 0
	v_pk_mul_f32 v[238:239], v[2:3], v[234:235]
	v_pk_mul_f32 v[240:241], v[4:5], v[234:235]
	v_pk_mul_f32 v[238:239], v[130:131], v[238:239]
	v_pk_mul_f32 v[240:241], v[132:133], v[240:241]
	v_pk_fma_f32 v[238:239], v[238:239], v[162:163], v[194:195]
	v_pk_fma_f32 v[240:241], v[240:241], v[164:165], v[196:197]
	v_cvt_pk_bf16_f32 v248, v238, v239
	v_cvt_pk_bf16_f32 v249, v240, v241
	v_pk_mul_f32 v[242:243], v[6:7], v[234:235]
	v_pk_mul_f32 v[244:245], v[8:9], v[234:235]
	v_pk_mul_f32 v[242:243], v[134:135], v[242:243]
	v_pk_mul_f32 v[244:245], v[136:137], v[244:245]
	v_pk_fma_f32 v[242:243], v[242:243], v[166:167], v[198:199]
	v_pk_fma_f32 v[244:245], v[244:245], v[168:169], v[200:201]
	v_cvt_pk_bf16_f32 v250, v242, v243
	v_cvt_pk_bf16_f32 v251, v244, v245
	global_store_dwordx4 v231, v[248:251], s[70:71]
	s_nop 1
	v_pk_mul_f32 v[238:239], v[10:11], v[234:235]
	v_pk_mul_f32 v[240:241], v[12:13], v[234:235]
	v_pk_mul_f32 v[238:239], v[138:139], v[238:239]
	v_pk_mul_f32 v[240:241], v[140:141], v[240:241]
	v_pk_fma_f32 v[238:239], v[238:239], v[170:171], v[202:203]
	v_pk_fma_f32 v[240:241], v[240:241], v[172:173], v[204:205]
	v_cvt_pk_bf16_f32 v248, v238, v239
	v_cvt_pk_bf16_f32 v249, v240, v241
	v_pk_mul_f32 v[242:243], v[14:15], v[234:235]
	v_pk_mul_f32 v[244:245], v[16:17], v[234:235]
	v_pk_mul_f32 v[242:243], v[142:143], v[242:243]
	v_pk_mul_f32 v[244:245], v[144:145], v[244:245]
	v_pk_fma_f32 v[242:243], v[242:243], v[174:175], v[206:207]
	v_pk_fma_f32 v[244:245], v[244:245], v[176:177], v[208:209]
	v_cvt_pk_bf16_f32 v250, v242, v243
	v_cvt_pk_bf16_f32 v251, v244, v245
	global_store_dwordx4 v231, v[248:251], s[70:71] offset:1024
	s_nop 1
	v_pk_mul_f32 v[238:239], v[18:19], v[234:235]
	v_pk_mul_f32 v[240:241], v[20:21], v[234:235]
	v_pk_mul_f32 v[238:239], v[146:147], v[238:239]
	v_pk_mul_f32 v[240:241], v[148:149], v[240:241]
	v_pk_fma_f32 v[238:239], v[238:239], v[178:179], v[210:211]
	v_pk_fma_f32 v[240:241], v[240:241], v[180:181], v[212:213]
	v_cvt_pk_bf16_f32 v248, v238, v239
	v_cvt_pk_bf16_f32 v249, v240, v241
	v_pk_mul_f32 v[242:243], v[22:23], v[234:235]
	v_pk_mul_f32 v[244:245], v[24:25], v[234:235]
	v_pk_mul_f32 v[242:243], v[150:151], v[242:243]
	v_pk_mul_f32 v[244:245], v[152:153], v[244:245]
	v_pk_fma_f32 v[242:243], v[242:243], v[182:183], v[214:215]
	v_pk_fma_f32 v[244:245], v[244:245], v[184:185], v[216:217]
	v_cvt_pk_bf16_f32 v250, v242, v243
	v_cvt_pk_bf16_f32 v251, v244, v245
	global_store_dwordx4 v231, v[248:251], s[70:71] offset:2048
	s_nop 1
	v_pk_mul_f32 v[238:239], v[26:27], v[234:235]
	v_pk_mul_f32 v[240:241], v[28:29], v[234:235]
	v_pk_mul_f32 v[238:239], v[154:155], v[238:239]
	v_pk_mul_f32 v[240:241], v[156:157], v[240:241]
	v_pk_fma_f32 v[238:239], v[238:239], v[186:187], v[218:219]
	v_pk_fma_f32 v[240:241], v[240:241], v[188:189], v[220:221]
	v_cvt_pk_bf16_f32 v248, v238, v239
	v_cvt_pk_bf16_f32 v249, v240, v241
	v_pk_mul_f32 v[242:243], v[30:31], v[234:235]
	v_pk_mul_f32 v[244:245], v[32:33], v[234:235]
	v_pk_mul_f32 v[242:243], v[158:159], v[242:243]
	v_pk_mul_f32 v[244:245], v[160:161], v[244:245]
	v_pk_fma_f32 v[242:243], v[242:243], v[226:227], v[222:223]
	v_pk_fma_f32 v[244:245], v[244:245], v[228:229], v[224:225]
	v_cvt_pk_bf16_f32 v250, v242, v243
	v_cvt_pk_bf16_f32 v251, v244, v245
	global_store_dwordx4 v231, v[248:251], s[70:71] offset:3072
	s_nop 1
	s_add_u32 s26, s14, 33562624
	s_addc_u32 s27, s15, 0
	s_add_u32 s24, s26, 0x1000
	s_addc_u32 s25, s27, 0
	global_load_dwordx4 v[2:5], v230, s[26:27] nt
	global_load_dwordx4 v[6:9], v230, s[26:27] offset:16 nt
	global_load_dwordx4 v[10:13], v230, s[26:27] offset:2048 nt
	global_load_dwordx4 v[14:17], v230, s[26:27] offset:2064 nt
	global_load_dwordx4 v[18:21], v230, s[24:25] nt
	global_load_dwordx4 v[22:25], v230, s[24:25] offset:16 nt
	global_load_dwordx4 v[26:29], v230, s[24:25] offset:2048 nt
	global_load_dwordx4 v[30:33], v230, s[24:25] offset:2064 nt
	s_waitcnt vmcnt(20)
	v_pk_mul_f32 v[232:233], v[34:35], v[34:35]
	v_pk_fma_f32 v[232:233], v[36:37], v[36:37], v[232:233]
	v_pk_fma_f32 v[232:233], v[38:39], v[38:39], v[232:233]
	v_pk_fma_f32 v[232:233], v[40:41], v[40:41], v[232:233]
	v_pk_fma_f32 v[232:233], v[42:43], v[42:43], v[232:233]
	v_pk_fma_f32 v[232:233], v[44:45], v[44:45], v[232:233]
	v_pk_fma_f32 v[232:233], v[46:47], v[46:47], v[232:233]
	v_pk_fma_f32 v[232:233], v[48:49], v[48:49], v[232:233]
	v_pk_fma_f32 v[232:233], v[50:51], v[50:51], v[232:233]
	v_pk_fma_f32 v[232:233], v[52:53], v[52:53], v[232:233]
	v_pk_fma_f32 v[232:233], v[54:55], v[54:55], v[232:233]
	v_pk_fma_f32 v[232:233], v[56:57], v[56:57], v[232:233]
	v_pk_fma_f32 v[232:233], v[58:59], v[58:59], v[232:233]
	v_pk_fma_f32 v[232:233], v[60:61], v[60:61], v[232:233]
	v_pk_fma_f32 v[232:233], v[62:63], v[62:63], v[232:233]
	v_pk_fma_f32 v[232:233], v[64:65], v[64:65], v[232:233]
	v_add_f32_e32 v232, v232, v233
	s_nop 1
	v_add_f32_dpp v232, v232, v232 quad_perm:[1,0,3,2] row_mask:0xf bank_mask:0xf
	s_nop 1
	v_add_f32_dpp v232, v232, v232 quad_perm:[2,3,0,1] row_mask:0xf bank_mask:0xf
	s_nop 1
	v_add_f32_dpp v232, v232, v232 row_half_mirror row_mask:0xf bank_mask:0xf
	s_nop 1
	v_add_f32_dpp v232, v232, v232 row_mirror row_mask:0xf bank_mask:0xf
	s_nop 1
	v_readlane_b32 s0, v232, 0
	v_readlane_b32 s1, v232, 16
	v_readlane_b32 s68, v232, 32
	v_readlane_b32 s69, v232, 48
	s_nop 3
	v_mov_b32_e32 v234, s0
	v_add_f32_e32 v234, s1, v234
	v_add_f32_e32 v234, s68, v234
	v_add_f32_e32 v234, s69, v234
	v_fmaak_f32 v234, v234, v246, 0x358637bd
	v_rsq_f32_e32 v234, v234
	s_nop 0
	v_mov_b32_e32 v235, v234
	s_add_u32 s70, s22, 4096
	s_addc_u32 s71, s23, 0
	v_pk_mul_f32 v[238:239], v[34:35], v[234:235]
	v_pk_mul_f32 v[240:241], v[36:37], v[234:235]
	v_pk_mul_f32 v[238:239], v[130:131], v[238:239]
	v_pk_mul_f32 v[240:241], v[132:133], v[240:241]
	v_pk_fma_f32 v[238:239], v[238:239], v[162:163], v[194:195]
	v_pk_fma_f32 v[240:241], v[240:241], v[164:165], v[196:197]
	v_cvt_pk_bf16_f32 v248, v238, v239
	v_cvt_pk_bf16_f32 v249, v240, v241
	v_pk_mul_f32 v[242:243], v[38:39], v[234:235]
	v_pk_mul_f32 v[244:245], v[40:41], v[234:235]
	v_pk_mul_f32 v[242:243], v[134:135], v[242:243]
	v_pk_mul_f32 v[244:245], v[136:137], v[244:245]
	v_pk_fma_f32 v[242:243], v[242:243], v[166:167], v[198:199]
	v_pk_fma_f32 v[244:245], v[244:245], v[168:169], v[200:201]
	v_cvt_pk_bf16_f32 v250, v242, v243
	v_cvt_pk_bf16_f32 v251, v244, v245
	global_store_dwordx4 v231, v[248:251], s[70:71]
	s_nop 1
	v_pk_mul_f32 v[238:239], v[42:43], v[234:235]
	v_pk_mul_f32 v[240:241], v[44:45], v[234:235]
	v_pk_mul_f32 v[238:239], v[138:139], v[238:239]
	v_pk_mul_f32 v[240:241], v[140:141], v[240:241]
	v_pk_fma_f32 v[238:239], v[238:239], v[170:171], v[202:203]
	v_pk_fma_f32 v[240:241], v[240:241], v[172:173], v[204:205]
	v_cvt_pk_bf16_f32 v248, v238, v239
	v_cvt_pk_bf16_f32 v249, v240, v241
	v_pk_mul_f32 v[242:243], v[46:47], v[234:235]
	v_pk_mul_f32 v[244:245], v[48:49], v[234:235]
	v_pk_mul_f32 v[242:243], v[142:143], v[242:243]
	v_pk_mul_f32 v[244:245], v[144:145], v[244:245]
	v_pk_fma_f32 v[242:243], v[242:243], v[174:175], v[206:207]
	v_pk_fma_f32 v[244:245], v[244:245], v[176:177], v[208:209]
	v_cvt_pk_bf16_f32 v250, v242, v243
	v_cvt_pk_bf16_f32 v251, v244, v245
	global_store_dwordx4 v231, v[248:251], s[70:71] offset:1024
	s_nop 1
	v_pk_mul_f32 v[238:239], v[50:51], v[234:235]
	v_pk_mul_f32 v[240:241], v[52:53], v[234:235]
	v_pk_mul_f32 v[238:239], v[146:147], v[238:239]
	v_pk_mul_f32 v[240:241], v[148:149], v[240:241]
	v_pk_fma_f32 v[238:239], v[238:239], v[178:179], v[210:211]
	v_pk_fma_f32 v[240:241], v[240:241], v[180:181], v[212:213]
	v_cvt_pk_bf16_f32 v248, v238, v239
	v_cvt_pk_bf16_f32 v249, v240, v241
	v_pk_mul_f32 v[242:243], v[54:55], v[234:235]
	v_pk_mul_f32 v[244:245], v[56:57], v[234:235]
	v_pk_mul_f32 v[242:243], v[150:151], v[242:243]
	v_pk_mul_f32 v[244:245], v[152:153], v[244:245]
	v_pk_fma_f32 v[242:243], v[242:243], v[182:183], v[214:215]
	v_pk_fma_f32 v[244:245], v[244:245], v[184:185], v[216:217]
	v_cvt_pk_bf16_f32 v250, v242, v243
	v_cvt_pk_bf16_f32 v251, v244, v245
	global_store_dwordx4 v231, v[248:251], s[70:71] offset:2048
	s_nop 1
	v_pk_mul_f32 v[238:239], v[58:59], v[234:235]
	v_pk_mul_f32 v[240:241], v[60:61], v[234:235]
	v_pk_mul_f32 v[238:239], v[154:155], v[238:239]
	v_pk_mul_f32 v[240:241], v[156:157], v[240:241]
	v_pk_fma_f32 v[238:239], v[238:239], v[186:187], v[218:219]
	v_pk_fma_f32 v[240:241], v[240:241], v[188:189], v[220:221]
	v_cvt_pk_bf16_f32 v248, v238, v239
	v_cvt_pk_bf16_f32 v249, v240, v241
	v_pk_mul_f32 v[242:243], v[62:63], v[234:235]
	v_pk_mul_f32 v[244:245], v[64:65], v[234:235]
	v_pk_mul_f32 v[242:243], v[158:159], v[242:243]
	v_pk_mul_f32 v[244:245], v[160:161], v[244:245]
	v_pk_fma_f32 v[242:243], v[242:243], v[226:227], v[222:223]
	v_pk_fma_f32 v[244:245], v[244:245], v[228:229], v[224:225]
	v_cvt_pk_bf16_f32 v250, v242, v243
	v_cvt_pk_bf16_f32 v251, v244, v245
	global_store_dwordx4 v231, v[248:251], s[70:71] offset:3072
	s_nop 1
	s_add_u32 s26, s16, 0
	s_addc_u32 s27, s17, 0
	s_add_u32 s24, s26, 0x1000
	s_addc_u32 s25, s27, 0
	global_load_dwordx4 v[34:37], v230, s[26:27] nt
	global_load_dwordx4 v[38:41], v230, s[26:27] offset:16 nt
	global_load_dwordx4 v[42:45], v230, s[26:27] offset:2048 nt
	global_load_dwordx4 v[46:49], v230, s[26:27] offset:2064 nt
	global_load_dwordx4 v[50:53], v230, s[24:25] nt
	global_load_dwordx4 v[54:57], v230, s[24:25] offset:16 nt
	global_load_dwordx4 v[58:61], v230, s[24:25] offset:2048 nt
	global_load_dwordx4 v[62:65], v230, s[24:25] offset:2064 nt
	s_waitcnt vmcnt(24)
	v_pk_mul_f32 v[232:233], v[66:67], v[66:67]
	v_pk_fma_f32 v[232:233], v[68:69], v[68:69], v[232:233]
	v_pk_fma_f32 v[232:233], v[70:71], v[70:71], v[232:233]
	v_pk_fma_f32 v[232:233], v[72:73], v[72:73], v[232:233]
	v_pk_fma_f32 v[232:233], v[74:75], v[74:75], v[232:233]
	v_pk_fma_f32 v[232:233], v[76:77], v[76:77], v[232:233]
	v_pk_fma_f32 v[232:233], v[78:79], v[78:79], v[232:233]
	v_pk_fma_f32 v[232:233], v[80:81], v[80:81], v[232:233]
	v_pk_fma_f32 v[232:233], v[82:83], v[82:83], v[232:233]
	v_pk_fma_f32 v[232:233], v[84:85], v[84:85], v[232:233]
	v_pk_fma_f32 v[232:233], v[86:87], v[86:87], v[232:233]
	v_pk_fma_f32 v[232:233], v[88:89], v[88:89], v[232:233]
	v_pk_fma_f32 v[232:233], v[90:91], v[90:91], v[232:233]
	v_pk_fma_f32 v[232:233], v[92:93], v[92:93], v[232:233]
	v_pk_fma_f32 v[232:233], v[94:95], v[94:95], v[232:233]
	v_pk_fma_f32 v[232:233], v[96:97], v[96:97], v[232:233]
	v_add_f32_e32 v232, v232, v233
	s_nop 1
	v_add_f32_dpp v232, v232, v232 quad_perm:[1,0,3,2] row_mask:0xf bank_mask:0xf
	s_nop 1
	v_add_f32_dpp v232, v232, v232 quad_perm:[2,3,0,1] row_mask:0xf bank_mask:0xf
	s_nop 1
	v_add_f32_dpp v232, v232, v232 row_half_mirror row_mask:0xf bank_mask:0xf
	s_nop 1
	v_add_f32_dpp v232, v232, v232 row_mirror row_mask:0xf bank_mask:0xf
	s_nop 1
	v_readlane_b32 s0, v232, 0
	v_readlane_b32 s1, v232, 16
	v_readlane_b32 s68, v232, 32
	v_readlane_b32 s69, v232, 48
	s_nop 3
	v_mov_b32_e32 v234, s0
	v_add_f32_e32 v234, s1, v234
	v_add_f32_e32 v234, s68, v234
	v_add_f32_e32 v234, s69, v234
	v_fmaak_f32 v234, v234, v246, 0x358637bd
	v_rsq_f32_e32 v234, v234
	s_nop 0
	v_mov_b32_e32 v235, v234
	s_add_u32 s70, s22, 16777216
	s_addc_u32 s71, s23, 0
	v_pk_mul_f32 v[238:239], v[66:67], v[234:235]
	v_pk_mul_f32 v[240:241], v[68:69], v[234:235]
	v_pk_mul_f32 v[238:239], v[130:131], v[238:239]
	v_pk_mul_f32 v[240:241], v[132:133], v[240:241]
	v_pk_fma_f32 v[238:239], v[238:239], v[162:163], v[194:195]
	v_pk_fma_f32 v[240:241], v[240:241], v[164:165], v[196:197]
	v_cvt_pk_bf16_f32 v248, v238, v239
	v_cvt_pk_bf16_f32 v249, v240, v241
	v_pk_mul_f32 v[242:243], v[70:71], v[234:235]
	v_pk_mul_f32 v[244:245], v[72:73], v[234:235]
	v_pk_mul_f32 v[242:243], v[134:135], v[242:243]
	v_pk_mul_f32 v[244:245], v[136:137], v[244:245]
	v_pk_fma_f32 v[242:243], v[242:243], v[166:167], v[198:199]
	v_pk_fma_f32 v[244:245], v[244:245], v[168:169], v[200:201]
	v_cvt_pk_bf16_f32 v250, v242, v243
	v_cvt_pk_bf16_f32 v251, v244, v245
	global_store_dwordx4 v231, v[248:251], s[70:71]
	s_nop 1
	v_pk_mul_f32 v[238:239], v[74:75], v[234:235]
	v_pk_mul_f32 v[240:241], v[76:77], v[234:235]
	v_pk_mul_f32 v[238:239], v[138:139], v[238:239]
	v_pk_mul_f32 v[240:241], v[140:141], v[240:241]
	v_pk_fma_f32 v[238:239], v[238:239], v[170:171], v[202:203]
	v_pk_fma_f32 v[240:241], v[240:241], v[172:173], v[204:205]
	v_cvt_pk_bf16_f32 v248, v238, v239
	v_cvt_pk_bf16_f32 v249, v240, v241
	v_pk_mul_f32 v[242:243], v[78:79], v[234:235]
	v_pk_mul_f32 v[244:245], v[80:81], v[234:235]
	v_pk_mul_f32 v[242:243], v[142:143], v[242:243]
	v_pk_mul_f32 v[244:245], v[144:145], v[244:245]
	v_pk_fma_f32 v[242:243], v[242:243], v[174:175], v[206:207]
	v_pk_fma_f32 v[244:245], v[244:245], v[176:177], v[208:209]
	v_cvt_pk_bf16_f32 v250, v242, v243
	v_cvt_pk_bf16_f32 v251, v244, v245
	global_store_dwordx4 v231, v[248:251], s[70:71] offset:1024
	s_nop 1
	v_pk_mul_f32 v[238:239], v[82:83], v[234:235]
	v_pk_mul_f32 v[240:241], v[84:85], v[234:235]
	v_pk_mul_f32 v[238:239], v[146:147], v[238:239]
	v_pk_mul_f32 v[240:241], v[148:149], v[240:241]
	v_pk_fma_f32 v[238:239], v[238:239], v[178:179], v[210:211]
	v_pk_fma_f32 v[240:241], v[240:241], v[180:181], v[212:213]
	v_cvt_pk_bf16_f32 v248, v238, v239
	v_cvt_pk_bf16_f32 v249, v240, v241
	v_pk_mul_f32 v[242:243], v[86:87], v[234:235]
	v_pk_mul_f32 v[244:245], v[88:89], v[234:235]
	v_pk_mul_f32 v[242:243], v[150:151], v[242:243]
	v_pk_mul_f32 v[244:245], v[152:153], v[244:245]
	v_pk_fma_f32 v[242:243], v[242:243], v[182:183], v[214:215]
	v_pk_fma_f32 v[244:245], v[244:245], v[184:185], v[216:217]
	v_cvt_pk_bf16_f32 v250, v242, v243
	v_cvt_pk_bf16_f32 v251, v244, v245
	global_store_dwordx4 v231, v[248:251], s[70:71] offset:2048
	s_nop 1
	v_pk_mul_f32 v[238:239], v[90:91], v[234:235]
	v_pk_mul_f32 v[240:241], v[92:93], v[234:235]
	v_pk_mul_f32 v[238:239], v[154:155], v[238:239]
	v_pk_mul_f32 v[240:241], v[156:157], v[240:241]
	v_pk_fma_f32 v[238:239], v[238:239], v[186:187], v[218:219]
	v_pk_fma_f32 v[240:241], v[240:241], v[188:189], v[220:221]
	v_cvt_pk_bf16_f32 v248, v238, v239
	v_cvt_pk_bf16_f32 v249, v240, v241
	v_pk_mul_f32 v[242:243], v[94:95], v[234:235]
	v_pk_mul_f32 v[244:245], v[96:97], v[234:235]
	v_pk_mul_f32 v[242:243], v[158:159], v[242:243]
	v_pk_mul_f32 v[244:245], v[160:161], v[244:245]
	v_pk_fma_f32 v[242:243], v[242:243], v[226:227], v[222:223]
	v_pk_fma_f32 v[244:245], v[244:245], v[228:229], v[224:225]
	v_cvt_pk_bf16_f32 v250, v242, v243
	v_cvt_pk_bf16_f32 v251, v244, v245
	global_store_dwordx4 v231, v[248:251], s[70:71] offset:3072
	s_nop 1
	s_add_u32 s26, s16, 8192
	s_addc_u32 s27, s17, 0
	s_add_u32 s24, s26, 0x1000
	s_addc_u32 s25, s27, 0
	global_load_dwordx4 v[66:69], v230, s[26:27] nt
	global_load_dwordx4 v[70:73], v230, s[26:27] offset:16 nt
	global_load_dwordx4 v[74:77], v230, s[26:27] offset:2048 nt
	global_load_dwordx4 v[78:81], v230, s[26:27] offset:2064 nt
	global_load_dwordx4 v[82:85], v230, s[24:25] nt
	global_load_dwordx4 v[86:89], v230, s[24:25] offset:16 nt
	global_load_dwordx4 v[90:93], v230, s[24:25] offset:2048 nt
	global_load_dwordx4 v[94:97], v230, s[24:25] offset:2064 nt
	s_waitcnt vmcnt(24)
	s_add_u32 s28, s18, 0
	s_lshr_b32 s29, s28, 6
	s_lshl_b32 s29, s29, 12
	s_add_u32 s29, s29, 0x80000
	s_add_u32 s30, s62, s29
	s_addc_u32 s31, s63, 0
	s_and_b32 s29, s28, 63
	s_add_u32 s29, s29, 16
	s_lshl_b32 s29, s29, 12
	s_add_u32 s29, s29, 0x80000
	s_add_u32 s36, s62, s29
	s_addc_u32 s37, s63, 0
	global_load_dwordx4 v[98:101], v230, s[30:31]
	global_load_dwordx4 v[102:105], v230, s[30:31] offset:16
	global_load_dwordx4 v[106:109], v230, s[30:31] offset:2048
	global_load_dwordx4 v[110:113], v230, s[30:31] offset:2064
	global_load_dwordx4 v[114:117], v230, s[36:37]
	global_load_dwordx4 v[118:121], v230, s[36:37] offset:16
	global_load_dwordx4 v[122:125], v230, s[36:37] offset:2048
	global_load_dwordx4 v[126:129], v230, s[36:37] offset:2064
	v_pk_mul_f32 v[232:233], v[2:3], v[2:3]
	v_pk_fma_f32 v[232:233], v[4:5], v[4:5], v[232:233]
	v_pk_fma_f32 v[232:233], v[6:7], v[6:7], v[232:233]
	v_pk_fma_f32 v[232:233], v[8:9], v[8:9], v[232:233]
	v_pk_fma_f32 v[232:233], v[10:11], v[10:11], v[232:233]
	v_pk_fma_f32 v[232:233], v[12:13], v[12:13], v[232:233]
	v_pk_fma_f32 v[232:233], v[14:15], v[14:15], v[232:233]
	v_pk_fma_f32 v[232:233], v[16:17], v[16:17], v[232:233]
	v_pk_fma_f32 v[232:233], v[18:19], v[18:19], v[232:233]
	v_pk_fma_f32 v[232:233], v[20:21], v[20:21], v[232:233]
	v_pk_fma_f32 v[232:233], v[22:23], v[22:23], v[232:233]
	v_pk_fma_f32 v[232:233], v[24:25], v[24:25], v[232:233]
	v_pk_fma_f32 v[232:233], v[26:27], v[26:27], v[232:233]
	v_pk_fma_f32 v[232:233], v[28:29], v[28:29], v[232:233]
	v_pk_fma_f32 v[232:233], v[30:31], v[30:31], v[232:233]
	v_pk_fma_f32 v[232:233], v[32:33], v[32:33], v[232:233]
	v_add_f32_e32 v232, v232, v233
	s_nop 1
	v_add_f32_dpp v232, v232, v232 quad_perm:[1,0,3,2] row_mask:0xf bank_mask:0xf
	s_nop 1
	v_add_f32_dpp v232, v232, v232 quad_perm:[2,3,0,1] row_mask:0xf bank_mask:0xf
	s_nop 1
	v_add_f32_dpp v232, v232, v232 row_half_mirror row_mask:0xf bank_mask:0xf
	s_nop 1
	v_add_f32_dpp v232, v232, v232 row_mirror row_mask:0xf bank_mask:0xf
	s_nop 1
	v_readlane_b32 s0, v232, 0
	v_readlane_b32 s1, v232, 16
	v_readlane_b32 s68, v232, 32
	v_readlane_b32 s69, v232, 48
	s_nop 3
	v_mov_b32_e32 v234, s0
	v_add_f32_e32 v234, s1, v234
	v_add_f32_e32 v234, s68, v234
	v_add_f32_e32 v234, s69, v234
	v_fmaak_f32 v234, v234, v246, 0x358637bd
	v_rsq_f32_e32 v234, v234
	s_nop 0
	v_mov_b32_e32 v235, v234
	s_add_u32 s70, s22, 16781312
	s_addc_u32 s71, s23, 0
	v_pk_mul_f32 v[238:239], v[2:3], v[234:235]
	v_pk_mul_f32 v[240:241], v[4:5], v[234:235]
	v_pk_mul_f32 v[238:239], v[130:131], v[238:239]
	v_pk_mul_f32 v[240:241], v[132:133], v[240:241]
	v_pk_fma_f32 v[238:239], v[238:239], v[162:163], v[194:195]
	v_pk_fma_f32 v[240:241], v[240:241], v[164:165], v[196:197]
	v_cvt_pk_bf16_f32 v248, v238, v239
	v_cvt_pk_bf16_f32 v249, v240, v241
	v_pk_mul_f32 v[242:243], v[6:7], v[234:235]
	v_pk_mul_f32 v[244:245], v[8:9], v[234:235]
	v_pk_mul_f32 v[242:243], v[134:135], v[242:243]
	v_pk_mul_f32 v[244:245], v[136:137], v[244:245]
	v_pk_fma_f32 v[242:243], v[242:243], v[166:167], v[198:199]
	v_pk_fma_f32 v[244:245], v[244:245], v[168:169], v[200:201]
	v_cvt_pk_bf16_f32 v250, v242, v243
	v_cvt_pk_bf16_f32 v251, v244, v245
	global_store_dwordx4 v231, v[248:251], s[70:71]
	s_nop 1
	v_pk_mul_f32 v[238:239], v[10:11], v[234:235]
	v_pk_mul_f32 v[240:241], v[12:13], v[234:235]
	v_pk_mul_f32 v[238:239], v[138:139], v[238:239]
	v_pk_mul_f32 v[240:241], v[140:141], v[240:241]
	v_pk_fma_f32 v[238:239], v[238:239], v[170:171], v[202:203]
	v_pk_fma_f32 v[240:241], v[240:241], v[172:173], v[204:205]
	v_cvt_pk_bf16_f32 v248, v238, v239
	v_cvt_pk_bf16_f32 v249, v240, v241
	v_pk_mul_f32 v[242:243], v[14:15], v[234:235]
	v_pk_mul_f32 v[244:245], v[16:17], v[234:235]
	v_pk_mul_f32 v[242:243], v[142:143], v[242:243]
	v_pk_mul_f32 v[244:245], v[144:145], v[244:245]
	v_pk_fma_f32 v[242:243], v[242:243], v[174:175], v[206:207]
	v_pk_fma_f32 v[244:245], v[244:245], v[176:177], v[208:209]
	v_cvt_pk_bf16_f32 v250, v242, v243
	v_cvt_pk_bf16_f32 v251, v244, v245
	global_store_dwordx4 v231, v[248:251], s[70:71] offset:1024
	s_nop 1
	v_pk_mul_f32 v[238:239], v[18:19], v[234:235]
	v_pk_mul_f32 v[240:241], v[20:21], v[234:235]
	v_pk_mul_f32 v[238:239], v[146:147], v[238:239]
	v_pk_mul_f32 v[240:241], v[148:149], v[240:241]
	v_pk_fma_f32 v[238:239], v[238:239], v[178:179], v[210:211]
	v_pk_fma_f32 v[240:241], v[240:241], v[180:181], v[212:213]
	v_cvt_pk_bf16_f32 v248, v238, v239
	v_cvt_pk_bf16_f32 v249, v240, v241
	v_pk_mul_f32 v[242:243], v[22:23], v[234:235]
	v_pk_mul_f32 v[244:245], v[24:25], v[234:235]
	v_pk_mul_f32 v[242:243], v[150:151], v[242:243]
	v_pk_mul_f32 v[244:245], v[152:153], v[244:245]
	v_pk_fma_f32 v[242:243], v[242:243], v[182:183], v[214:215]
	v_pk_fma_f32 v[244:245], v[244:245], v[184:185], v[216:217]
	v_cvt_pk_bf16_f32 v250, v242, v243
	v_cvt_pk_bf16_f32 v251, v244, v245
	global_store_dwordx4 v231, v[248:251], s[70:71] offset:2048
	s_nop 1
	v_pk_mul_f32 v[238:239], v[26:27], v[234:235]
	v_pk_mul_f32 v[240:241], v[28:29], v[234:235]
	v_pk_mul_f32 v[238:239], v[154:155], v[238:239]
	v_pk_mul_f32 v[240:241], v[156:157], v[240:241]
	v_pk_fma_f32 v[238:239], v[238:239], v[186:187], v[218:219]
	v_pk_fma_f32 v[240:241], v[240:241], v[188:189], v[220:221]
	v_cvt_pk_bf16_f32 v248, v238, v239
	v_cvt_pk_bf16_f32 v249, v240, v241
	v_pk_mul_f32 v[242:243], v[30:31], v[234:235]
	v_pk_mul_f32 v[244:245], v[32:33], v[234:235]
	v_pk_mul_f32 v[242:243], v[158:159], v[242:243]
	v_pk_mul_f32 v[244:245], v[160:161], v[244:245]
	v_pk_fma_f32 v[242:243], v[242:243], v[226:227], v[222:223]
	v_pk_fma_f32 v[244:245], v[244:245], v[228:229], v[224:225]
	v_cvt_pk_bf16_f32 v250, v242, v243
	v_cvt_pk_bf16_f32 v251, v244, v245
	global_store_dwordx4 v231, v[248:251], s[70:71] offset:3072
	s_nop 1
	s_add_u32 s38, s19, 1
	s_mul_i32 s38, s38, 0xc000
	s_add_u32 s38, s62, s38
	s_addc_u32 s39, s63, 0
	s_add_u32 s40, s38, 0x2000
	s_addc_u32 s41, s39, 0
	s_add_u32 s64, s38, 0x1000
	s_addc_u32 s65, s39, 0
	s_add_u32 s66, s40, 0x1000
	s_addc_u32 s67, s41, 0
	global_load_dwordx4 v[194:197], v230, s[38:39]
	global_load_dwordx4 v[162:165], v230, s[40:41]
	global_load_dwordx4 v[198:201], v230, s[38:39] offset:16
	global_load_dwordx4 v[166:169], v230, s[40:41] offset:16
	global_load_dwordx4 v[202:205], v230, s[38:39] offset:2048
	global_load_dwordx4 v[170:173], v230, s[40:41] offset:2048
	global_load_dwordx4 v[206:209], v230, s[38:39] offset:2064
	global_load_dwordx4 v[174:177], v230, s[40:41] offset:2064
	global_load_dwordx4 v[210:213], v230, s[64:65]
	global_load_dwordx4 v[178:181], v230, s[66:67]
	global_load_dwordx4 v[214:217], v230, s[64:65] offset:16
	global_load_dwordx4 v[182:185], v230, s[66:67] offset:16
	global_load_dwordx4 v[218:221], v230, s[64:65] offset:2048
	global_load_dwordx4 v[186:189], v230, s[66:67] offset:2048
	global_load_dwordx4 v[222:225], v230, s[64:65] offset:2064
	global_load_dwordx4 v[226:229], v230, s[66:67] offset:2064
	s_add_u32 s26, s16, 33554432
	s_addc_u32 s27, s17, 0
	s_add_u32 s24, s26, 0x1000
	s_addc_u32 s25, s27, 0
	global_load_dwordx4 v[2:5], v230, s[26:27] nt
	global_load_dwordx4 v[6:9], v230, s[26:27] offset:16 nt
	global_load_dwordx4 v[10:13], v230, s[26:27] offset:2048 nt
	global_load_dwordx4 v[14:17], v230, s[26:27] offset:2064 nt
	global_load_dwordx4 v[18:21], v230, s[24:25] nt
	global_load_dwordx4 v[22:25], v230, s[24:25] offset:16 nt
	global_load_dwordx4 v[26:29], v230, s[24:25] offset:2048 nt
	global_load_dwordx4 v[30:33], v230, s[24:25] offset:2064 nt
	s_waitcnt vmcnt(28)
	v_pk_add_f32 v[34:35], v[34:35], v[98:99]
	v_pk_add_f32 v[36:37], v[36:37], v[100:101]
	v_pk_add_f32 v[38:39], v[38:39], v[102:103]
	v_pk_add_f32 v[40:41], v[40:41], v[104:105]
	v_pk_add_f32 v[42:43], v[42:43], v[106:107]
	v_pk_add_f32 v[44:45], v[44:45], v[108:109]
	v_pk_add_f32 v[46:47], v[46:47], v[110:111]
	v_pk_add_f32 v[48:49], v[48:49], v[112:113]
	v_pk_add_f32 v[50:51], v[50:51], v[114:115]
	v_pk_add_f32 v[52:53], v[52:53], v[116:117]
	v_pk_add_f32 v[54:55], v[54:55], v[118:119]
	v_pk_add_f32 v[56:57], v[56:57], v[120:121]
	v_pk_add_f32 v[58:59], v[58:59], v[122:123]
	v_pk_add_f32 v[60:61], v[60:61], v[124:125]
	v_pk_add_f32 v[62:63], v[62:63], v[126:127]
	v_pk_add_f32 v[64:65], v[64:65], v[128:129]
	s_add_u32 s28, s18, 1
	s_lshr_b32 s29, s28, 6
	s_lshl_b32 s29, s29, 12
	s_add_u32 s29, s29, 0x80000
	s_add_u32 s30, s62, s29
	s_addc_u32 s31, s63, 0
	s_and_b32 s29, s28, 63
	s_add_u32 s29, s29, 16
	s_lshl_b32 s29, s29, 12
	s_add_u32 s29, s29, 0x80000
	s_add_u32 s36, s62, s29
	s_addc_u32 s37, s63, 0
	global_load_dwordx4 v[98:101], v230, s[30:31]
	global_load_dwordx4 v[102:105], v230, s[30:31] offset:16
	global_load_dwordx4 v[106:109], v230, s[30:31] offset:2048
	global_load_dwordx4 v[110:113], v230, s[30:31] offset:2064
	global_load_dwordx4 v[114:117], v230, s[36:37]
	global_load_dwordx4 v[118:121], v230, s[36:37] offset:16
	global_load_dwordx4 v[122:125], v230, s[36:37] offset:2048
	global_load_dwordx4 v[126:129], v230, s[36:37] offset:2064
	v_pk_mul_f32 v[232:233], v[34:35], v[34:35]
	v_pk_fma_f32 v[232:233], v[36:37], v[36:37], v[232:233]
	v_pk_fma_f32 v[232:233], v[38:39], v[38:39], v[232:233]
	v_pk_fma_f32 v[232:233], v[40:41], v[40:41], v[232:233]
	v_pk_fma_f32 v[232:233], v[42:43], v[42:43], v[232:233]
	v_pk_fma_f32 v[232:233], v[44:45], v[44:45], v[232:233]
	v_pk_fma_f32 v[232:233], v[46:47], v[46:47], v[232:233]
	v_pk_fma_f32 v[232:233], v[48:49], v[48:49], v[232:233]
	v_pk_fma_f32 v[232:233], v[50:51], v[50:51], v[232:233]
	v_pk_fma_f32 v[232:233], v[52:53], v[52:53], v[232:233]
	v_pk_fma_f32 v[232:233], v[54:55], v[54:55], v[232:233]
	v_pk_fma_f32 v[232:233], v[56:57], v[56:57], v[232:233]
	v_pk_fma_f32 v[232:233], v[58:59], v[58:59], v[232:233]
	v_pk_fma_f32 v[232:233], v[60:61], v[60:61], v[232:233]
	v_pk_fma_f32 v[232:233], v[62:63], v[62:63], v[232:233]
	v_pk_fma_f32 v[232:233], v[64:65], v[64:65], v[232:233]
	v_add_f32_e32 v232, v232, v233
	s_nop 1
	v_add_f32_dpp v232, v232, v232 quad_perm:[1,0,3,2] row_mask:0xf bank_mask:0xf
	s_nop 1
	v_add_f32_dpp v232, v232, v232 quad_perm:[2,3,0,1] row_mask:0xf bank_mask:0xf
	s_nop 1
	v_add_f32_dpp v232, v232, v232 row_half_mirror row_mask:0xf bank_mask:0xf
	s_nop 1
	v_add_f32_dpp v232, v232, v232 row_mirror row_mask:0xf bank_mask:0xf
	s_nop 1
	v_readlane_b32 s0, v232, 0
	v_readlane_b32 s1, v232, 16
	v_readlane_b32 s68, v232, 32
	v_readlane_b32 s69, v232, 48
	s_nop 3
	v_mov_b32_e32 v234, s0
	v_add_f32_e32 v234, s1, v234
	v_add_f32_e32 v234, s68, v234
	v_add_f32_e32 v234, s69, v234
	v_fmaak_f32 v234, v234, v246, 0x358637bd
	v_rsq_f32_e32 v234, v234
	s_nop 0
	v_mov_b32_e32 v235, v234
	s_waitcnt vmcnt(16)
	v_pk_add_f32 v[162:163], v[162:163], 1.0 op_sel_hi:[1,0]
	v_pk_add_f32 v[164:165], v[164:165], 1.0 op_sel_hi:[1,0]
	v_pk_add_f32 v[166:167], v[166:167], 1.0 op_sel_hi:[1,0]
	v_pk_add_f32 v[168:169], v[168:169], 1.0 op_sel_hi:[1,0]
	v_pk_add_f32 v[170:171], v[170:171], 1.0 op_sel_hi:[1,0]
	v_pk_add_f32 v[172:173], v[172:173], 1.0 op_sel_hi:[1,0]
	v_pk_add_f32 v[174:175], v[174:175], 1.0 op_sel_hi:[1,0]
	v_pk_add_f32 v[176:177], v[176:177], 1.0 op_sel_hi:[1,0]
	v_pk_add_f32 v[178:179], v[178:179], 1.0 op_sel_hi:[1,0]
	v_pk_add_f32 v[180:181], v[180:181], 1.0 op_sel_hi:[1,0]
	v_pk_add_f32 v[182:183], v[182:183], 1.0 op_sel_hi:[1,0]
	v_pk_add_f32 v[184:185], v[184:185], 1.0 op_sel_hi:[1,0]
	v_pk_add_f32 v[186:187], v[186:187], 1.0 op_sel_hi:[1,0]
	v_pk_add_f32 v[188:189], v[188:189], 1.0 op_sel_hi:[1,0]
	v_pk_add_f32 v[226:227], v[226:227], 1.0 op_sel_hi:[1,0]
	v_pk_add_f32 v[228:229], v[228:229], 1.0 op_sel_hi:[1,0]
	s_add_u32 s70, s22, 33554432
	s_addc_u32 s71, s23, 0
	v_pk_mul_f32 v[238:239], v[34:35], v[234:235]
	v_pk_mul_f32 v[240:241], v[36:37], v[234:235]
	v_pk_mul_f32 v[238:239], v[130:131], v[238:239]
	v_pk_mul_f32 v[240:241], v[132:133], v[240:241]
	v_pk_fma_f32 v[238:239], v[238:239], v[162:163], v[194:195]
	v_pk_fma_f32 v[240:241], v[240:241], v[164:165], v[196:197]
	v_cvt_pk_bf16_f32 v248, v238, v239
	v_cvt_pk_bf16_f32 v249, v240, v241
	v_pk_mul_f32 v[242:243], v[38:39], v[234:235]
	v_pk_mul_f32 v[244:245], v[40:41], v[234:235]
	v_pk_mul_f32 v[242:243], v[134:135], v[242:243]
	v_pk_mul_f32 v[244:245], v[136:137], v[244:245]
	v_pk_fma_f32 v[242:243], v[242:243], v[166:167], v[198:199]
	v_pk_fma_f32 v[244:245], v[244:245], v[168:169], v[200:201]
	v_cvt_pk_bf16_f32 v250, v242, v243
	v_cvt_pk_bf16_f32 v251, v244, v245
	global_store_dwordx4 v231, v[248:251], s[70:71]
	s_nop 1
	v_pk_mul_f32 v[238:239], v[42:43], v[234:235]
	v_pk_mul_f32 v[240:241], v[44:45], v[234:235]
	v_pk_mul_f32 v[238:239], v[138:139], v[238:239]
	v_pk_mul_f32 v[240:241], v[140:141], v[240:241]
	v_pk_fma_f32 v[238:239], v[238:239], v[170:171], v[202:203]
	v_pk_fma_f32 v[240:241], v[240:241], v[172:173], v[204:205]
	v_cvt_pk_bf16_f32 v248, v238, v239
	v_cvt_pk_bf16_f32 v249, v240, v241
	v_pk_mul_f32 v[242:243], v[46:47], v[234:235]
	v_pk_mul_f32 v[244:245], v[48:49], v[234:235]
	v_pk_mul_f32 v[242:243], v[142:143], v[242:243]
	v_pk_mul_f32 v[244:245], v[144:145], v[244:245]
	v_pk_fma_f32 v[242:243], v[242:243], v[174:175], v[206:207]
	v_pk_fma_f32 v[244:245], v[244:245], v[176:177], v[208:209]
	v_cvt_pk_bf16_f32 v250, v242, v243
	v_cvt_pk_bf16_f32 v251, v244, v245
	global_store_dwordx4 v231, v[248:251], s[70:71] offset:1024
	s_nop 1
	v_pk_mul_f32 v[238:239], v[50:51], v[234:235]
	v_pk_mul_f32 v[240:241], v[52:53], v[234:235]
	v_pk_mul_f32 v[238:239], v[146:147], v[238:239]
	v_pk_mul_f32 v[240:241], v[148:149], v[240:241]
	v_pk_fma_f32 v[238:239], v[238:239], v[178:179], v[210:211]
	v_pk_fma_f32 v[240:241], v[240:241], v[180:181], v[212:213]
	v_cvt_pk_bf16_f32 v248, v238, v239
	v_cvt_pk_bf16_f32 v249, v240, v241
	v_pk_mul_f32 v[242:243], v[54:55], v[234:235]
	v_pk_mul_f32 v[244:245], v[56:57], v[234:235]
	v_pk_mul_f32 v[242:243], v[150:151], v[242:243]
	v_pk_mul_f32 v[244:245], v[152:153], v[244:245]
	v_pk_fma_f32 v[242:243], v[242:243], v[182:183], v[214:215]
	v_pk_fma_f32 v[244:245], v[244:245], v[184:185], v[216:217]
	v_cvt_pk_bf16_f32 v250, v242, v243
	v_cvt_pk_bf16_f32 v251, v244, v245
	global_store_dwordx4 v231, v[248:251], s[70:71] offset:2048
	s_nop 1
	v_pk_mul_f32 v[238:239], v[58:59], v[234:235]
	v_pk_mul_f32 v[240:241], v[60:61], v[234:235]
	v_pk_mul_f32 v[238:239], v[154:155], v[238:239]
	v_pk_mul_f32 v[240:241], v[156:157], v[240:241]
	v_pk_fma_f32 v[238:239], v[238:239], v[186:187], v[218:219]
	v_pk_fma_f32 v[240:241], v[240:241], v[188:189], v[220:221]
	v_cvt_pk_bf16_f32 v248, v238, v239
	v_cvt_pk_bf16_f32 v249, v240, v241
	v_pk_mul_f32 v[242:243], v[62:63], v[234:235]
	v_pk_mul_f32 v[244:245], v[64:65], v[234:235]
	v_pk_mul_f32 v[242:243], v[158:159], v[242:243]
	v_pk_mul_f32 v[244:245], v[160:161], v[244:245]
	v_pk_fma_f32 v[242:243], v[242:243], v[226:227], v[222:223]
	v_pk_fma_f32 v[244:245], v[244:245], v[228:229], v[224:225]
	v_cvt_pk_bf16_f32 v250, v242, v243
	v_cvt_pk_bf16_f32 v251, v244, v245
	global_store_dwordx4 v231, v[248:251], s[70:71] offset:3072
	s_nop 1
	s_add_u32 s26, s16, 33562624
	s_addc_u32 s27, s17, 0
	s_add_u32 s24, s26, 0x1000
	s_addc_u32 s25, s27, 0
	global_load_dwordx4 v[34:37], v230, s[26:27] nt
	global_load_dwordx4 v[38:41], v230, s[26:27] offset:16 nt
	global_load_dwordx4 v[42:45], v230, s[26:27] offset:2048 nt
	global_load_dwordx4 v[46:49], v230, s[26:27] offset:2064 nt
	global_load_dwordx4 v[50:53], v230, s[24:25] nt
	global_load_dwordx4 v[54:57], v230, s[24:25] offset:16 nt
	global_load_dwordx4 v[58:61], v230, s[24:25] offset:2048 nt
	global_load_dwordx4 v[62:65], v230, s[24:25] offset:2064 nt
	s_waitcnt vmcnt(12)
	v_pk_add_f32 v[66:67], v[66:67], v[98:99]
	v_pk_add_f32 v[68:69], v[68:69], v[100:101]
	v_pk_add_f32 v[70:71], v[70:71], v[102:103]
	v_pk_add_f32 v[72:73], v[72:73], v[104:105]
	v_pk_add_f32 v[74:75], v[74:75], v[106:107]
	v_pk_add_f32 v[76:77], v[76:77], v[108:109]
	v_pk_add_f32 v[78:79], v[78:79], v[110:111]
	v_pk_add_f32 v[80:81], v[80:81], v[112:113]
	v_pk_add_f32 v[82:83], v[82:83], v[114:115]
	v_pk_add_f32 v[84:85], v[84:85], v[116:117]
	v_pk_add_f32 v[86:87], v[86:87], v[118:119]
	v_pk_add_f32 v[88:89], v[88:89], v[120:121]
	v_pk_add_f32 v[90:91], v[90:91], v[122:123]
	v_pk_add_f32 v[92:93], v[92:93], v[124:125]
	v_pk_add_f32 v[94:95], v[94:95], v[126:127]
	v_pk_add_f32 v[96:97], v[96:97], v[128:129]
	s_add_u32 s28, s18, 0
	s_lshr_b32 s29, s28, 6
	s_lshl_b32 s29, s29, 12
	s_add_u32 s29, s29, 0x80000
	s_add_u32 s30, s62, s29
	s_addc_u32 s31, s63, 0
	s_and_b32 s29, s28, 63
	s_add_u32 s29, s29, 16
	s_lshl_b32 s29, s29, 12
	s_add_u32 s29, s29, 0x80000
	s_add_u32 s36, s62, s29
	s_addc_u32 s37, s63, 0
	global_load_dwordx4 v[98:101], v230, s[30:31]
	global_load_dwordx4 v[102:105], v230, s[30:31] offset:16
	global_load_dwordx4 v[106:109], v230, s[30:31] offset:2048
	global_load_dwordx4 v[110:113], v230, s[30:31] offset:2064
	global_load_dwordx4 v[114:117], v230, s[36:37]
	global_load_dwordx4 v[118:121], v230, s[36:37] offset:16
	global_load_dwordx4 v[122:125], v230, s[36:37] offset:2048
	global_load_dwordx4 v[126:129], v230, s[36:37] offset:2064
	v_pk_mul_f32 v[232:233], v[66:67], v[66:67]
	v_pk_fma_f32 v[232:233], v[68:69], v[68:69], v[232:233]
	v_pk_fma_f32 v[232:233], v[70:71], v[70:71], v[232:233]
	v_pk_fma_f32 v[232:233], v[72:73], v[72:73], v[232:233]
	v_pk_fma_f32 v[232:233], v[74:75], v[74:75], v[232:233]
	v_pk_fma_f32 v[232:233], v[76:77], v[76:77], v[232:233]
	v_pk_fma_f32 v[232:233], v[78:79], v[78:79], v[232:233]
	v_pk_fma_f32 v[232:233], v[80:81], v[80:81], v[232:233]
	v_pk_fma_f32 v[232:233], v[82:83], v[82:83], v[232:233]
	v_pk_fma_f32 v[232:233], v[84:85], v[84:85], v[232:233]
	v_pk_fma_f32 v[232:233], v[86:87], v[86:87], v[232:233]
	v_pk_fma_f32 v[232:233], v[88:89], v[88:89], v[232:233]
	v_pk_fma_f32 v[232:233], v[90:91], v[90:91], v[232:233]
	v_pk_fma_f32 v[232:233], v[92:93], v[92:93], v[232:233]
	v_pk_fma_f32 v[232:233], v[94:95], v[94:95], v[232:233]
	v_pk_fma_f32 v[232:233], v[96:97], v[96:97], v[232:233]
	v_add_f32_e32 v232, v232, v233
	s_nop 1
	v_add_f32_dpp v232, v232, v232 quad_perm:[1,0,3,2] row_mask:0xf bank_mask:0xf
	s_nop 1
	v_add_f32_dpp v232, v232, v232 quad_perm:[2,3,0,1] row_mask:0xf bank_mask:0xf
	s_nop 1
	v_add_f32_dpp v232, v232, v232 row_half_mirror row_mask:0xf bank_mask:0xf
	s_nop 1
	v_add_f32_dpp v232, v232, v232 row_mirror row_mask:0xf bank_mask:0xf
	s_nop 1
	v_readlane_b32 s0, v232, 0
	v_readlane_b32 s1, v232, 16
	v_readlane_b32 s68, v232, 32
	v_readlane_b32 s69, v232, 48
	s_nop 3
	v_mov_b32_e32 v234, s0
	v_add_f32_e32 v234, s1, v234
	v_add_f32_e32 v234, s68, v234
	v_add_f32_e32 v234, s69, v234
	v_fmaak_f32 v234, v234, v246, 0x358637bd
	v_rsq_f32_e32 v234, v234
	s_nop 0
	v_mov_b32_e32 v235, v234
	s_add_u32 s70, s22, 33558528
	s_addc_u32 s71, s23, 0
	v_pk_mul_f32 v[238:239], v[66:67], v[234:235]
	v_pk_mul_f32 v[240:241], v[68:69], v[234:235]
	v_pk_mul_f32 v[238:239], v[130:131], v[238:239]
	v_pk_mul_f32 v[240:241], v[132:133], v[240:241]
	v_pk_fma_f32 v[238:239], v[238:239], v[162:163], v[194:195]
	v_pk_fma_f32 v[240:241], v[240:241], v[164:165], v[196:197]
	v_cvt_pk_bf16_f32 v248, v238, v239
	v_cvt_pk_bf16_f32 v249, v240, v241
	v_pk_mul_f32 v[242:243], v[70:71], v[234:235]
	v_pk_mul_f32 v[244:245], v[72:73], v[234:235]
	v_pk_mul_f32 v[242:243], v[134:135], v[242:243]
	v_pk_mul_f32 v[244:245], v[136:137], v[244:245]
	v_pk_fma_f32 v[242:243], v[242:243], v[166:167], v[198:199]
	v_pk_fma_f32 v[244:245], v[244:245], v[168:169], v[200:201]
	v_cvt_pk_bf16_f32 v250, v242, v243
	v_cvt_pk_bf16_f32 v251, v244, v245
	global_store_dwordx4 v231, v[248:251], s[70:71]
	s_nop 1
	v_pk_mul_f32 v[238:239], v[74:75], v[234:235]
	v_pk_mul_f32 v[240:241], v[76:77], v[234:235]
	v_pk_mul_f32 v[238:239], v[138:139], v[238:239]
	v_pk_mul_f32 v[240:241], v[140:141], v[240:241]
	v_pk_fma_f32 v[238:239], v[238:239], v[170:171], v[202:203]
	v_pk_fma_f32 v[240:241], v[240:241], v[172:173], v[204:205]
	v_cvt_pk_bf16_f32 v248, v238, v239
	v_cvt_pk_bf16_f32 v249, v240, v241
	v_pk_mul_f32 v[242:243], v[78:79], v[234:235]
	v_pk_mul_f32 v[244:245], v[80:81], v[234:235]
	v_pk_mul_f32 v[242:243], v[142:143], v[242:243]
	v_pk_mul_f32 v[244:245], v[144:145], v[244:245]
	v_pk_fma_f32 v[242:243], v[242:243], v[174:175], v[206:207]
	v_pk_fma_f32 v[244:245], v[244:245], v[176:177], v[208:209]
	v_cvt_pk_bf16_f32 v250, v242, v243
	v_cvt_pk_bf16_f32 v251, v244, v245
	global_store_dwordx4 v231, v[248:251], s[70:71] offset:1024
	s_nop 1
	v_pk_mul_f32 v[238:239], v[82:83], v[234:235]
	v_pk_mul_f32 v[240:241], v[84:85], v[234:235]
	v_pk_mul_f32 v[238:239], v[146:147], v[238:239]
	v_pk_mul_f32 v[240:241], v[148:149], v[240:241]
	v_pk_fma_f32 v[238:239], v[238:239], v[178:179], v[210:211]
	v_pk_fma_f32 v[240:241], v[240:241], v[180:181], v[212:213]
	v_cvt_pk_bf16_f32 v248, v238, v239
	v_cvt_pk_bf16_f32 v249, v240, v241
	v_pk_mul_f32 v[242:243], v[86:87], v[234:235]
	v_pk_mul_f32 v[244:245], v[88:89], v[234:235]
	v_pk_mul_f32 v[242:243], v[150:151], v[242:243]
	v_pk_mul_f32 v[244:245], v[152:153], v[244:245]
	v_pk_fma_f32 v[242:243], v[242:243], v[182:183], v[214:215]
	v_pk_fma_f32 v[244:245], v[244:245], v[184:185], v[216:217]
	v_cvt_pk_bf16_f32 v250, v242, v243
	v_cvt_pk_bf16_f32 v251, v244, v245
	global_store_dwordx4 v231, v[248:251], s[70:71] offset:2048
	s_nop 1
	v_pk_mul_f32 v[238:239], v[90:91], v[234:235]
	v_pk_mul_f32 v[240:241], v[92:93], v[234:235]
	v_pk_mul_f32 v[238:239], v[154:155], v[238:239]
	v_pk_mul_f32 v[240:241], v[156:157], v[240:241]
	v_pk_fma_f32 v[238:239], v[238:239], v[186:187], v[218:219]
	v_pk_fma_f32 v[240:241], v[240:241], v[188:189], v[220:221]
	v_cvt_pk_bf16_f32 v248, v238, v239
	v_cvt_pk_bf16_f32 v249, v240, v241
	v_pk_mul_f32 v[242:243], v[94:95], v[234:235]
	v_pk_mul_f32 v[244:245], v[96:97], v[234:235]
	v_pk_mul_f32 v[242:243], v[158:159], v[242:243]
	v_pk_mul_f32 v[244:245], v[160:161], v[244:245]
	v_pk_fma_f32 v[242:243], v[242:243], v[226:227], v[222:223]
	v_pk_fma_f32 v[244:245], v[244:245], v[228:229], v[224:225]
	v_cvt_pk_bf16_f32 v250, v242, v243
	v_cvt_pk_bf16_f32 v251, v244, v245
	global_store_dwordx4 v231, v[248:251], s[70:71] offset:3072
	s_nop 1
	s_add_u32 s38, s19, 5
	s_mul_i32 s38, s38, 0xc000
	s_add_u32 s38, s62, s38
	s_addc_u32 s39, s63, 0
	s_add_u32 s40, s38, 0x2000
	s_addc_u32 s41, s39, 0
	s_add_u32 s64, s38, 0x1000
	s_addc_u32 s65, s39, 0
	s_add_u32 s66, s40, 0x1000
	s_addc_u32 s67, s41, 0
	global_load_dwordx4 v[194:197], v230, s[38:39]
	global_load_dwordx4 v[162:165], v230, s[40:41]
	global_load_dwordx4 v[198:201], v230, s[38:39] offset:16
	global_load_dwordx4 v[166:169], v230, s[40:41] offset:16
	global_load_dwordx4 v[202:205], v230, s[38:39] offset:2048
	global_load_dwordx4 v[170:173], v230, s[40:41] offset:2048
	global_load_dwordx4 v[206:209], v230, s[38:39] offset:2064
	global_load_dwordx4 v[174:177], v230, s[40:41] offset:2064
	global_load_dwordx4 v[210:213], v230, s[64:65]
	global_load_dwordx4 v[178:181], v230, s[66:67]
	global_load_dwordx4 v[214:217], v230, s[64:65] offset:16
	global_load_dwordx4 v[182:185], v230, s[66:67] offset:16
	global_load_dwordx4 v[218:221], v230, s[64:65] offset:2048
	global_load_dwordx4 v[186:189], v230, s[66:67] offset:2048
	global_load_dwordx4 v[222:225], v230, s[64:65] offset:2064
	global_load_dwordx4 v[226:229], v230, s[66:67] offset:2064
	s_waitcnt vmcnt(20)
	v_pk_add_f32 v[2:3], v[2:3], v[98:99]
	v_pk_add_f32 v[4:5], v[4:5], v[100:101]
	v_pk_add_f32 v[6:7], v[6:7], v[102:103]
	v_pk_add_f32 v[8:9], v[8:9], v[104:105]
	v_pk_add_f32 v[10:11], v[10:11], v[106:107]
	v_pk_add_f32 v[12:13], v[12:13], v[108:109]
	v_pk_add_f32 v[14:15], v[14:15], v[110:111]
	v_pk_add_f32 v[16:17], v[16:17], v[112:113]
	v_pk_add_f32 v[18:19], v[18:19], v[114:115]
	v_pk_add_f32 v[20:21], v[20:21], v[116:117]
	v_pk_add_f32 v[22:23], v[22:23], v[118:119]
	v_pk_add_f32 v[24:25], v[24:25], v[120:121]
	v_pk_add_f32 v[26:27], v[26:27], v[122:123]
	v_pk_add_f32 v[28:29], v[28:29], v[124:125]
	v_pk_add_f32 v[30:31], v[30:31], v[126:127]
	v_pk_add_f32 v[32:33], v[32:33], v[128:129]
	s_add_u32 s28, s18, 1
	s_lshr_b32 s29, s28, 6
	s_lshl_b32 s29, s29, 12
	s_add_u32 s29, s29, 0x80000
	s_add_u32 s30, s62, s29
	s_addc_u32 s31, s63, 0
	s_and_b32 s29, s28, 63
	s_add_u32 s29, s29, 16
	s_lshl_b32 s29, s29, 12
	s_add_u32 s29, s29, 0x80000
	s_add_u32 s36, s62, s29
	s_addc_u32 s37, s63, 0
	global_load_dwordx4 v[98:101], v230, s[30:31]
	global_load_dwordx4 v[102:105], v230, s[30:31] offset:16
	global_load_dwordx4 v[106:109], v230, s[30:31] offset:2048
	global_load_dwordx4 v[110:113], v230, s[30:31] offset:2064
	global_load_dwordx4 v[114:117], v230, s[36:37]
	global_load_dwordx4 v[118:121], v230, s[36:37] offset:16
	global_load_dwordx4 v[122:125], v230, s[36:37] offset:2048
	global_load_dwordx4 v[126:129], v230, s[36:37] offset:2064
	v_pk_mul_f32 v[232:233], v[2:3], v[2:3]
	v_pk_fma_f32 v[232:233], v[4:5], v[4:5], v[232:233]
	v_pk_fma_f32 v[232:233], v[6:7], v[6:7], v[232:233]
	v_pk_fma_f32 v[232:233], v[8:9], v[8:9], v[232:233]
	v_pk_fma_f32 v[232:233], v[10:11], v[10:11], v[232:233]
	v_pk_fma_f32 v[232:233], v[12:13], v[12:13], v[232:233]
	v_pk_fma_f32 v[232:233], v[14:15], v[14:15], v[232:233]
	v_pk_fma_f32 v[232:233], v[16:17], v[16:17], v[232:233]
	v_pk_fma_f32 v[232:233], v[18:19], v[18:19], v[232:233]
	v_pk_fma_f32 v[232:233], v[20:21], v[20:21], v[232:233]
	v_pk_fma_f32 v[232:233], v[22:23], v[22:23], v[232:233]
	v_pk_fma_f32 v[232:233], v[24:25], v[24:25], v[232:233]
	v_pk_fma_f32 v[232:233], v[26:27], v[26:27], v[232:233]
	v_pk_fma_f32 v[232:233], v[28:29], v[28:29], v[232:233]
	v_pk_fma_f32 v[232:233], v[30:31], v[30:31], v[232:233]
	v_pk_fma_f32 v[232:233], v[32:33], v[32:33], v[232:233]
	v_add_f32_e32 v232, v232, v233
	s_nop 1
	v_add_f32_dpp v232, v232, v232 quad_perm:[1,0,3,2] row_mask:0xf bank_mask:0xf
	s_nop 1
	v_add_f32_dpp v232, v232, v232 quad_perm:[2,3,0,1] row_mask:0xf bank_mask:0xf
	s_nop 1
	v_add_f32_dpp v232, v232, v232 row_half_mirror row_mask:0xf bank_mask:0xf
	s_nop 1
	v_add_f32_dpp v232, v232, v232 row_mirror row_mask:0xf bank_mask:0xf
	s_nop 1
	v_readlane_b32 s0, v232, 0
	v_readlane_b32 s1, v232, 16
	v_readlane_b32 s68, v232, 32
	v_readlane_b32 s69, v232, 48
	s_nop 3
	v_mov_b32_e32 v234, s0
	v_add_f32_e32 v234, s1, v234
	v_add_f32_e32 v234, s68, v234
	v_add_f32_e32 v234, s69, v234
	v_fmaak_f32 v234, v234, v246, 0x358637bd
	v_rsq_f32_e32 v234, v234
	s_nop 0
	v_mov_b32_e32 v235, v234
	s_waitcnt vmcnt(8)
	v_pk_add_f32 v[162:163], v[162:163], 1.0 op_sel_hi:[1,0]
	v_pk_add_f32 v[164:165], v[164:165], 1.0 op_sel_hi:[1,0]
	v_pk_add_f32 v[166:167], v[166:167], 1.0 op_sel_hi:[1,0]
	v_pk_add_f32 v[168:169], v[168:169], 1.0 op_sel_hi:[1,0]
	v_pk_add_f32 v[170:171], v[170:171], 1.0 op_sel_hi:[1,0]
	v_pk_add_f32 v[172:173], v[172:173], 1.0 op_sel_hi:[1,0]
	v_pk_add_f32 v[174:175], v[174:175], 1.0 op_sel_hi:[1,0]
	v_pk_add_f32 v[176:177], v[176:177], 1.0 op_sel_hi:[1,0]
	v_pk_add_f32 v[178:179], v[178:179], 1.0 op_sel_hi:[1,0]
	v_pk_add_f32 v[180:181], v[180:181], 1.0 op_sel_hi:[1,0]
	v_pk_add_f32 v[182:183], v[182:183], 1.0 op_sel_hi:[1,0]
	v_pk_add_f32 v[184:185], v[184:185], 1.0 op_sel_hi:[1,0]
	v_pk_add_f32 v[186:187], v[186:187], 1.0 op_sel_hi:[1,0]
	v_pk_add_f32 v[188:189], v[188:189], 1.0 op_sel_hi:[1,0]
	v_pk_add_f32 v[226:227], v[226:227], 1.0 op_sel_hi:[1,0]
	v_pk_add_f32 v[228:229], v[228:229], 1.0 op_sel_hi:[1,0]
	s_add_u32 s70, s22, 50331648
	s_addc_u32 s71, s23, 0
	v_pk_mul_f32 v[238:239], v[2:3], v[234:235]
	v_pk_mul_f32 v[240:241], v[4:5], v[234:235]
	v_pk_mul_f32 v[238:239], v[130:131], v[238:239]
	v_pk_mul_f32 v[240:241], v[132:133], v[240:241]
	v_pk_fma_f32 v[238:239], v[238:239], v[162:163], v[194:195]
	v_pk_fma_f32 v[240:241], v[240:241], v[164:165], v[196:197]
	v_cvt_pk_bf16_f32 v248, v238, v239
	v_cvt_pk_bf16_f32 v249, v240, v241
	v_pk_mul_f32 v[242:243], v[6:7], v[234:235]
	v_pk_mul_f32 v[244:245], v[8:9], v[234:235]
	v_pk_mul_f32 v[242:243], v[134:135], v[242:243]
	v_pk_mul_f32 v[244:245], v[136:137], v[244:245]
	v_pk_fma_f32 v[242:243], v[242:243], v[166:167], v[198:199]
	v_pk_fma_f32 v[244:245], v[244:245], v[168:169], v[200:201]
	v_cvt_pk_bf16_f32 v250, v242, v243
	v_cvt_pk_bf16_f32 v251, v244, v245
	global_store_dwordx4 v231, v[248:251], s[70:71]
	s_nop 1
	v_pk_mul_f32 v[238:239], v[10:11], v[234:235]
	v_pk_mul_f32 v[240:241], v[12:13], v[234:235]
	v_pk_mul_f32 v[238:239], v[138:139], v[238:239]
	v_pk_mul_f32 v[240:241], v[140:141], v[240:241]
	v_pk_fma_f32 v[238:239], v[238:239], v[170:171], v[202:203]
	v_pk_fma_f32 v[240:241], v[240:241], v[172:173], v[204:205]
	v_cvt_pk_bf16_f32 v248, v238, v239
	v_cvt_pk_bf16_f32 v249, v240, v241
	v_pk_mul_f32 v[242:243], v[14:15], v[234:235]
	v_pk_mul_f32 v[244:245], v[16:17], v[234:235]
	v_pk_mul_f32 v[242:243], v[142:143], v[242:243]
	v_pk_mul_f32 v[244:245], v[144:145], v[244:245]
	v_pk_fma_f32 v[242:243], v[242:243], v[174:175], v[206:207]
	v_pk_fma_f32 v[244:245], v[244:245], v[176:177], v[208:209]
	v_cvt_pk_bf16_f32 v250, v242, v243
	v_cvt_pk_bf16_f32 v251, v244, v245
	global_store_dwordx4 v231, v[248:251], s[70:71] offset:1024
	s_nop 1
	v_pk_mul_f32 v[238:239], v[18:19], v[234:235]
	v_pk_mul_f32 v[240:241], v[20:21], v[234:235]
	v_pk_mul_f32 v[238:239], v[146:147], v[238:239]
	v_pk_mul_f32 v[240:241], v[148:149], v[240:241]
	v_pk_fma_f32 v[238:239], v[238:239], v[178:179], v[210:211]
	v_pk_fma_f32 v[240:241], v[240:241], v[180:181], v[212:213]
	v_cvt_pk_bf16_f32 v248, v238, v239
	v_cvt_pk_bf16_f32 v249, v240, v241
	v_pk_mul_f32 v[242:243], v[22:23], v[234:235]
	v_pk_mul_f32 v[244:245], v[24:25], v[234:235]
	v_pk_mul_f32 v[242:243], v[150:151], v[242:243]
	v_pk_mul_f32 v[244:245], v[152:153], v[244:245]
	v_pk_fma_f32 v[242:243], v[242:243], v[182:183], v[214:215]
	v_pk_fma_f32 v[244:245], v[244:245], v[184:185], v[216:217]
	v_cvt_pk_bf16_f32 v250, v242, v243
	v_cvt_pk_bf16_f32 v251, v244, v245
	global_store_dwordx4 v231, v[248:251], s[70:71] offset:2048
	s_nop 1
	v_pk_mul_f32 v[238:239], v[26:27], v[234:235]
	v_pk_mul_f32 v[240:241], v[28:29], v[234:235]
	v_pk_mul_f32 v[238:239], v[154:155], v[238:239]
	v_pk_mul_f32 v[240:241], v[156:157], v[240:241]
	v_pk_fma_f32 v[238:239], v[238:239], v[186:187], v[218:219]
	v_pk_fma_f32 v[240:241], v[240:241], v[188:189], v[220:221]
	v_cvt_pk_bf16_f32 v248, v238, v239
	v_cvt_pk_bf16_f32 v249, v240, v241
	v_pk_mul_f32 v[242:243], v[30:31], v[234:235]
	v_pk_mul_f32 v[244:245], v[32:33], v[234:235]
	v_pk_mul_f32 v[242:243], v[158:159], v[242:243]
	v_pk_mul_f32 v[244:245], v[160:161], v[244:245]
	v_pk_fma_f32 v[242:243], v[242:243], v[226:227], v[222:223]
	v_pk_fma_f32 v[244:245], v[244:245], v[228:229], v[224:225]
	v_cvt_pk_bf16_f32 v250, v242, v243
	v_cvt_pk_bf16_f32 v251, v244, v245
	global_store_dwordx4 v231, v[248:251], s[70:71] offset:3072
	s_nop 1
	s_waitcnt vmcnt(4)
	v_pk_add_f32 v[34:35], v[34:35], v[98:99]
	v_pk_add_f32 v[36:37], v[36:37], v[100:101]
	v_pk_add_f32 v[38:39], v[38:39], v[102:103]
	v_pk_add_f32 v[40:41], v[40:41], v[104:105]
	v_pk_add_f32 v[42:43], v[42:43], v[106:107]
	v_pk_add_f32 v[44:45], v[44:45], v[108:109]
	v_pk_add_f32 v[46:47], v[46:47], v[110:111]
	v_pk_add_f32 v[48:49], v[48:49], v[112:113]
	v_pk_add_f32 v[50:51], v[50:51], v[114:115]
	v_pk_add_f32 v[52:53], v[52:53], v[116:117]
	v_pk_add_f32 v[54:55], v[54:55], v[118:119]
	v_pk_add_f32 v[56:57], v[56:57], v[120:121]
	v_pk_add_f32 v[58:59], v[58:59], v[122:123]
	v_pk_add_f32 v[60:61], v[60:61], v[124:125]
	v_pk_add_f32 v[62:63], v[62:63], v[126:127]
	v_pk_add_f32 v[64:65], v[64:65], v[128:129]
	v_pk_mul_f32 v[232:233], v[34:35], v[34:35]
	v_pk_fma_f32 v[232:233], v[36:37], v[36:37], v[232:233]
	v_pk_fma_f32 v[232:233], v[38:39], v[38:39], v[232:233]
	v_pk_fma_f32 v[232:233], v[40:41], v[40:41], v[232:233]
	v_pk_fma_f32 v[232:233], v[42:43], v[42:43], v[232:233]
	v_pk_fma_f32 v[232:233], v[44:45], v[44:45], v[232:233]
	v_pk_fma_f32 v[232:233], v[46:47], v[46:47], v[232:233]
	v_pk_fma_f32 v[232:233], v[48:49], v[48:49], v[232:233]
	v_pk_fma_f32 v[232:233], v[50:51], v[50:51], v[232:233]
	v_pk_fma_f32 v[232:233], v[52:53], v[52:53], v[232:233]
	v_pk_fma_f32 v[232:233], v[54:55], v[54:55], v[232:233]
	v_pk_fma_f32 v[232:233], v[56:57], v[56:57], v[232:233]
	v_pk_fma_f32 v[232:233], v[58:59], v[58:59], v[232:233]
	v_pk_fma_f32 v[232:233], v[60:61], v[60:61], v[232:233]
	v_pk_fma_f32 v[232:233], v[62:63], v[62:63], v[232:233]
	v_pk_fma_f32 v[232:233], v[64:65], v[64:65], v[232:233]
	v_add_f32_e32 v232, v232, v233
	s_nop 1
	v_add_f32_dpp v232, v232, v232 quad_perm:[1,0,3,2] row_mask:0xf bank_mask:0xf
	s_nop 1
	v_add_f32_dpp v232, v232, v232 quad_perm:[2,3,0,1] row_mask:0xf bank_mask:0xf
	s_nop 1
	v_add_f32_dpp v232, v232, v232 row_half_mirror row_mask:0xf bank_mask:0xf
	s_nop 1
	v_add_f32_dpp v232, v232, v232 row_mirror row_mask:0xf bank_mask:0xf
	s_nop 1
	v_readlane_b32 s0, v232, 0
	v_readlane_b32 s1, v232, 16
	v_readlane_b32 s68, v232, 32
	v_readlane_b32 s69, v232, 48
	s_nop 3
	v_mov_b32_e32 v234, s0
	v_add_f32_e32 v234, s1, v234
	v_add_f32_e32 v234, s68, v234
	v_add_f32_e32 v234, s69, v234
	v_fmaak_f32 v234, v234, v246, 0x358637bd
	v_rsq_f32_e32 v234, v234
	s_nop 0
	v_mov_b32_e32 v235, v234
	s_add_u32 s70, s22, 50335744
	s_addc_u32 s71, s23, 0
	v_pk_mul_f32 v[238:239], v[34:35], v[234:235]
	v_pk_mul_f32 v[240:241], v[36:37], v[234:235]
	v_pk_mul_f32 v[238:239], v[130:131], v[238:239]
	v_pk_mul_f32 v[240:241], v[132:133], v[240:241]
	v_pk_fma_f32 v[238:239], v[238:239], v[162:163], v[194:195]
	v_pk_fma_f32 v[240:241], v[240:241], v[164:165], v[196:197]
	v_cvt_pk_bf16_f32 v248, v238, v239
	v_cvt_pk_bf16_f32 v249, v240, v241
	v_pk_mul_f32 v[242:243], v[38:39], v[234:235]
	v_pk_mul_f32 v[244:245], v[40:41], v[234:235]
	v_pk_mul_f32 v[242:243], v[134:135], v[242:243]
	v_pk_mul_f32 v[244:245], v[136:137], v[244:245]
	v_pk_fma_f32 v[242:243], v[242:243], v[166:167], v[198:199]
	v_pk_fma_f32 v[244:245], v[244:245], v[168:169], v[200:201]
	v_cvt_pk_bf16_f32 v250, v242, v243
	v_cvt_pk_bf16_f32 v251, v244, v245
	global_store_dwordx4 v231, v[248:251], s[70:71]
	s_nop 1
	v_pk_mul_f32 v[238:239], v[42:43], v[234:235]
	v_pk_mul_f32 v[240:241], v[44:45], v[234:235]
	v_pk_mul_f32 v[238:239], v[138:139], v[238:239]
	v_pk_mul_f32 v[240:241], v[140:141], v[240:241]
	v_pk_fma_f32 v[238:239], v[238:239], v[170:171], v[202:203]
	v_pk_fma_f32 v[240:241], v[240:241], v[172:173], v[204:205]
	v_cvt_pk_bf16_f32 v248, v238, v239
	v_cvt_pk_bf16_f32 v249, v240, v241
	v_pk_mul_f32 v[242:243], v[46:47], v[234:235]
	v_pk_mul_f32 v[244:245], v[48:49], v[234:235]
	v_pk_mul_f32 v[242:243], v[142:143], v[242:243]
	v_pk_mul_f32 v[244:245], v[144:145], v[244:245]
	v_pk_fma_f32 v[242:243], v[242:243], v[174:175], v[206:207]
	v_pk_fma_f32 v[244:245], v[244:245], v[176:177], v[208:209]
	v_cvt_pk_bf16_f32 v250, v242, v243
	v_cvt_pk_bf16_f32 v251, v244, v245
	global_store_dwordx4 v231, v[248:251], s[70:71] offset:1024
	s_nop 1
	v_pk_mul_f32 v[238:239], v[50:51], v[234:235]
	v_pk_mul_f32 v[240:241], v[52:53], v[234:235]
	v_pk_mul_f32 v[238:239], v[146:147], v[238:239]
	v_pk_mul_f32 v[240:241], v[148:149], v[240:241]
	v_pk_fma_f32 v[238:239], v[238:239], v[178:179], v[210:211]
	v_pk_fma_f32 v[240:241], v[240:241], v[180:181], v[212:213]
	v_cvt_pk_bf16_f32 v248, v238, v239
	v_cvt_pk_bf16_f32 v249, v240, v241
	v_pk_mul_f32 v[242:243], v[54:55], v[234:235]
	v_pk_mul_f32 v[244:245], v[56:57], v[234:235]
	v_pk_mul_f32 v[242:243], v[150:151], v[242:243]
	v_pk_mul_f32 v[244:245], v[152:153], v[244:245]
	v_pk_fma_f32 v[242:243], v[242:243], v[182:183], v[214:215]
	v_pk_fma_f32 v[244:245], v[244:245], v[184:185], v[216:217]
	v_cvt_pk_bf16_f32 v250, v242, v243
	v_cvt_pk_bf16_f32 v251, v244, v245
	global_store_dwordx4 v231, v[248:251], s[70:71] offset:2048
	s_nop 1
	v_pk_mul_f32 v[238:239], v[58:59], v[234:235]
	v_pk_mul_f32 v[240:241], v[60:61], v[234:235]
	v_pk_mul_f32 v[238:239], v[154:155], v[238:239]
	v_pk_mul_f32 v[240:241], v[156:157], v[240:241]
	v_pk_fma_f32 v[238:239], v[238:239], v[186:187], v[218:219]
	v_pk_fma_f32 v[240:241], v[240:241], v[188:189], v[220:221]
	v_cvt_pk_bf16_f32 v248, v238, v239
	v_cvt_pk_bf16_f32 v249, v240, v241
	v_pk_mul_f32 v[242:243], v[62:63], v[234:235]
	v_pk_mul_f32 v[244:245], v[64:65], v[234:235]
	v_pk_mul_f32 v[242:243], v[158:159], v[242:243]
	v_pk_mul_f32 v[244:245], v[160:161], v[244:245]
	v_pk_fma_f32 v[242:243], v[242:243], v[226:227], v[222:223]
	v_pk_fma_f32 v[244:245], v[244:245], v[228:229], v[224:225]
	v_cvt_pk_bf16_f32 v250, v242, v243
	v_cvt_pk_bf16_f32 v251, v244, v245
	global_store_dwordx4 v231, v[248:251], s[70:71] offset:3072
	s_nop 1
	s_branch .Lr1_pad_end
	s_nop 0
	s_nop 0
	s_nop 0
	s_nop 0
	s_nop 0
	s_nop 0
	s_nop 0
	s_nop 0
	s_nop 0
	s_nop 0
	s_nop 0
	s_nop 0
	s_nop 0
	s_nop 0
	s_nop 0
	s_nop 0
	s_nop 0
	s_nop 0
	s_nop 0
	s_nop 0
.Lr1_pad_end:
.LBB0_180:
	s_mov_b32 s89, s34
